# layer-1 w_in GEMM main tiles: XCDs 4 decode positions apart (was 6); layer 0 stays at 6
# speedup vs baseline: 1.0066x; 1.0018x over previous
.Lgi_sk_rm:
	s_and_b32 s0, s57, 7
	s_lshr_b32 s1, s57, 3
	s_cmpk_ge_u32 s1, 192
	s_cbranch_scc1 .Lgi_sk_nr
	s_mul_i32 s57, s0, 190
	s_add_u32 s1, s1, s57
	s_mul_i32 s57, s1, 0x5556
	s_lshr_b32 s57, s57, 22
	s_mul_i32 s57, s57, 192
	s_sub_u32 s1, s1, s57
